# v85 + mLSTM scan: qn-section n-vector reads hoisted, seg-D/F single LDS reads issued earlier
# baseline (speedup 1.0000x reference)
.Lpf_skip:
.LBB0_209:
	v_add_u32_e32 v202, s85, v214
	v_add_u32_e32 v219, s85, v213
	v_add_u32_e32 v236, s85, v212
	ds_read_b128 v[120:123], v202 offset:34816
	ds_read_b128 v[124:127], v219
	ds_read_b128 v[220:223], v219 offset:4352
	ds_read_b128 v[224:227], v219 offset:8704
	ds_read_b128 v[228:231], v219 offset:13056
	ds_read_b128 v[232:235], v202
	v_add_u32_e32 v245, 0x1dc00, v236
	v_add_u32_e32 v236, 0x1ed00, v236
	ds_read_b128 v[246:249], v245
	ds_read_b128 v[236:239], v236
	ds_read_b128 v[250:253], v202 offset:39168
	s_add_i32 s85, s85, 64
	s_cmpk_eq_i32 s85, 0x100
	s_waitcnt lgkmcnt(7)
	v_mfma_f32_16x16x32_bf16 v[116:119], v[120:123], v[124:127], v[116:119]
	s_waitcnt lgkmcnt(6)
	v_mfma_f32_16x16x32_bf16 v[112:115], v[120:123], v[220:223], v[112:115]
	s_waitcnt lgkmcnt(5)
	v_mfma_f32_16x16x32_bf16 v[104:107], v[120:123], v[224:227], v[104:107]
	s_waitcnt lgkmcnt(4)
	v_mfma_f32_16x16x32_bf16 v[96:99], v[120:123], v[228:231], v[96:99]
	ds_read_b128 v[120:123], v202 offset:4352
	s_waitcnt lgkmcnt(3)
	v_mfma_f32_16x16x32_bf16 v[84:87], v[232:235], v[246:249], v[84:87]
	s_waitcnt lgkmcnt(2)
	v_mfma_f32_16x16x32_bf16 v[80:83], v[232:235], v[236:239], v[80:83]
	s_waitcnt lgkmcnt(1)
	v_mfma_f32_16x16x32_bf16 v[108:111], v[250:253], v[124:127], v[108:111]
	v_mfma_f32_16x16x32_bf16 v[100:103], v[250:253], v[220:223], v[100:103]
	v_mfma_f32_16x16x32_bf16 v[92:95], v[250:253], v[224:227], v[92:95]
	v_mfma_f32_16x16x32_bf16 v[88:91], v[250:253], v[228:231], v[88:91]
	s_waitcnt lgkmcnt(0)
	v_mfma_f32_16x16x32_bf16 v[76:79], v[120:123], v[246:249], v[76:79]
	v_mfma_f32_16x16x32_bf16 v[72:75], v[120:123], v[236:239], v[72:75]
	s_cbranch_scc0 .LBB0_209
	ds_read_b128 v[120:123], v169
	ds_read_b128 v[124:127], v169 offset:16
	ds_read_b128 v[220:223], v169 offset:32
	ds_read_b128 v[224:227], v169 offset:48
	ds_read_b128 v[228:231], v170
	ds_read_b128 v[232:235], v170 offset:16
	ds_read_b128 v[236:239], v170 offset:32
	ds_read_b128 v[240:243], v170 offset:48
	ds_read_b128 v[246:249], v170 offset:64
	ds_read_b128 v[250:253], v170 offset:80
	s_waitcnt lgkmcnt(9)
	v_lshlrev_b32_e32 v202, 16, v120
	v_and_b32_e32 v120, 0xffff0000, v120
	s_waitcnt lgkmcnt(5)
	v_mul_f32_e32 v120, v229, v120
	v_fmac_f32_e32 v120, v228, v202
	v_lshlrev_b32_e32 v202, 16, v121
	v_fmac_f32_e32 v120, v230, v202
	v_and_b32_e32 v121, 0xffff0000, v121
	v_fmac_f32_e32 v120, v231, v121
	v_lshlrev_b32_e32 v121, 16, v122
	s_waitcnt lgkmcnt(4)
	v_fmac_f32_e32 v120, v232, v121
	v_and_b32_e32 v121, 0xffff0000, v122
	v_fmac_f32_e32 v120, v233, v121
	v_lshlrev_b32_e32 v121, 16, v123
	v_fmac_f32_e32 v120, v234, v121
	v_and_b32_e32 v121, 0xffff0000, v123
	v_fmac_f32_e32 v120, v235, v121
	v_and_b32_e32 v121, 0xffff0000, v124
	v_add_f32_e32 v202, 0, v120
	v_lshlrev_b32_e32 v120, 16, v124
	s_waitcnt lgkmcnt(3)
	v_mul_f32_e32 v124, v237, v121
	v_fmac_f32_e32 v124, v236, v120
	v_lshlrev_b32_e32 v120, 16, v125
	v_fmac_f32_e32 v124, v238, v120
	v_and_b32_e32 v120, 0xffff0000, v125
	v_fmac_f32_e32 v124, v239, v120
	v_lshlrev_b32_e32 v120, 16, v126
	s_waitcnt lgkmcnt(2)
	v_fmac_f32_e32 v124, v240, v120
	v_and_b32_e32 v120, 0xffff0000, v126
	v_fmac_f32_e32 v124, v241, v120
	v_lshlrev_b32_e32 v120, 16, v127
	v_fmac_f32_e32 v124, v242, v120
	v_and_b32_e32 v120, 0xffff0000, v127
	v_fmac_f32_e32 v124, v243, v120
	ds_read_b128 v[120:123], v170 offset:96
	v_add_f32_e32 v202, v202, v124
	ds_read_b128 v[124:127], v170 offset:112
	v_lshlrev_b32_e32 v219, 16, v220
	v_and_b32_e32 v220, 0xffff0000, v220
	s_waitcnt lgkmcnt(2)
	v_mul_f32_e32 v220, v247, v220
	v_fmac_f32_e32 v220, v246, v219
	v_lshlrev_b32_e32 v245, 16, v221
	v_fmac_f32_e32 v220, v248, v245
	v_and_b32_e32 v245, 0xffff0000, v221
	v_fmac_f32_e32 v220, v249, v245
	v_lshlrev_b32_e32 v245, 16, v222
	s_nop 0
	v_fmac_f32_e32 v220, v250, v245
	v_and_b32_e32 v245, 0xffff0000, v222
	v_fmac_f32_e32 v220, v251, v245
	v_lshlrev_b32_e32 v245, 16, v223
	v_fmac_f32_e32 v220, v252, v245
	v_and_b32_e32 v245, 0xffff0000, v223
	v_fmac_f32_e32 v220, v253, v245
	s_nop 0
	s_nop 0
	v_add_f32_e32 v202, v202, v220
	v_and_b32_e32 v220, 0xffff0000, v224
	v_lshlrev_b32_e32 v219, 16, v224
	s_waitcnt lgkmcnt(1)
	v_mul_f32_e32 v121, v121, v220
	v_fmac_f32_e32 v121, v120, v219
	v_lshlrev_b32_e32 v120, 16, v225
	v_fmac_f32_e32 v121, v122, v120
	v_and_b32_e32 v120, 0xffff0000, v225
	v_fmac_f32_e32 v121, v123, v120
	v_lshlrev_b32_e32 v120, 16, v226
	s_waitcnt lgkmcnt(0)
	v_fmac_f32_e32 v121, v124, v120
	v_and_b32_e32 v120, 0xffff0000, v226
	v_fmac_f32_e32 v121, v125, v120
	v_lshlrev_b32_e32 v120, 16, v227
	v_fmac_f32_e32 v121, v126, v120
	v_and_b32_e32 v120, 0xffff0000, v227
	v_fmac_f32_e32 v121, v127, v120
	v_add_f32_e32 v120, v202, v121
	s_nop 1
	v_add_f32_dpp v120, v120, v120 quad_perm:[1,0,3,2] row_mask:0xf bank_mask:0xf
	s_waitcnt lgkmcnt(0)
	s_nop 1
	v_add_f32_dpp v120, v120, v120 quad_perm:[2,3,0,1] row_mask:0xf bank_mask:0xf
	s_and_saveexec_b64 s[86:87], s[6:7]
	s_cbranch_execz .LBB0_212
	s_waitcnt lgkmcnt(0)
	s_nop 0
	ds_write_b32 v173, v120

.LBB0_224:
	s_or_b64 exec, exec, s[86:87]
	v_mul_f32_e32 v117, v117, v220
	v_mul_f32_e32 v118, v118, v221
	v_mul_f32_e32 v104, v104, v235
	v_mul_f32_e32 v220, v94, v241
	v_mul_f32_e32 v221, v95, v242
	v_mul_f32_e32 v94, v96, v124
	v_mul_f32_e32 v95, v97, v125
	v_mul_f32_e32 v96, v98, v126
	v_mul_f32_e32 v108, v108, v223
	v_mul_f32_e32 v109, v109, v224
	v_mul_f32_e32 v105, v105, v236
	v_mul_f32_e32 v202, v92, v239
	v_mul_f32_e32 v97, v99, v127
	v_cvt_pk_bf16_f32 v92, v104, v105
	v_cvt_pk_bf16_f32 v94, v94, v95
	v_cvt_pk_bf16_f32 v95, v96, v97
	v_cvt_pk_bf16_f32 v96, v108, v109
	v_add_u32_e32 v104, 0x8800, v215
	v_mul_f32_e32 v116, v116, v219
	v_mul_f32_e32 v119, v119, v222
	v_mul_f32_e32 v110, v110, v225
	v_mul_f32_e32 v111, v111, v226
	v_mul_f32_e32 v112, v112, v227
	v_mul_f32_e32 v113, v113, v228
	v_mul_f32_e32 v98, v88, v120
	v_mul_f32_e32 v99, v89, v121
	v_mul_f32_e32 v120, v90, v122
	s_waitcnt lgkmcnt(0)
	s_barrier
	v_cvt_pk_bf16_f32 v88, v116, v117
	v_cvt_pk_bf16_f32 v89, v118, v119
	v_cvt_pk_bf16_f32 v90, v112, v113
	v_cvt_pk_bf16_f32 v97, v110, v111
	ds_write2_b64 v104, v[88:89], v[96:97] offset1:4
	v_add_u32_e32 v96, 0x9800, v215
	v_mul_f32_e32 v114, v114, v229
	v_mul_f32_e32 v115, v115, v230
	v_mul_f32_e32 v100, v100, v231
	v_mul_f32_e32 v101, v101, v232
	v_mul_f32_e32 v102, v102, v233
	v_mul_f32_e32 v103, v103, v234
	v_mul_f32_e32 v121, v91, v123
	v_cvt_pk_bf16_f32 v91, v114, v115
	v_cvt_pk_bf16_f32 v88, v100, v101
	v_cvt_pk_bf16_f32 v89, v102, v103
	ds_write2_b64 v96, v[90:91], v[88:89] offset0:32 offset1:36
	v_add_u32_e32 v90, 0xa800, v215
	v_mul_f32_e32 v106, v106, v237
	v_mul_f32_e32 v107, v107, v238
	v_mul_f32_e32 v219, v93, v240
	v_cvt_pk_bf16_f32 v93, v106, v107
	v_cvt_pk_bf16_f32 v88, v202, v219
	v_cvt_pk_bf16_f32 v89, v220, v221
	ds_write2_b64 v90, v[92:93], v[88:89] offset0:64 offset1:68
	v_add_u32_e32 v90, 0xb800, v215
	v_cvt_pk_bf16_f32 v88, v98, v99
	v_cvt_pk_bf16_f32 v89, v120, v121
	ds_write2_b64 v90, v[94:95], v[88:89] offset0:96 offset1:100
	s_and_saveexec_b64 s[86:87], s[0:1]
	s_cbranch_execz .LBB0_226
	ds_read_b32 v94, v177
	ds_read_b32 v95, v178
	ds_read2st64_b32 v[88:89], v179 offset1:2
	ds_read2st64_b32 v[90:91], v179 offset0:4 offset1:6
	ds_read_b32 v245, v180
	s_waitcnt lgkmcnt(2)
	v_mov_b32_e32 v92, v88
	s_waitcnt lgkmcnt(1)
	v_mov_b32_e32 v93, v90
	v_mov_b32_e32 v90, v89
	v_pk_add_f32 v[88:89], v[92:93], v[90:91]
	s_nop 0
	v_add_f32_e32 v88, v88, v89
	s_nop 0
	v_fmac_f32_e32 v88, v94, v95
	s_waitcnt lgkmcnt(0)
	v_max_f32_e32 v89, v245, v245
	v_max_f32_e64 v88, |v88|, v89
	v_div_scale_f32 v89, s[90:91], v88, v88, 1.0
	v_rcp_f32_e32 v90, v89
	s_nop 0
	v_fma_f32 v91, -v89, v90, 1.0
	v_fmac_f32_e32 v90, v91, v90
	v_div_scale_f32 v91, vcc, 1.0, v88, 1.0
	v_mul_f32_e32 v92, v91, v90
	v_fma_f32 v93, -v89, v92, v91
	v_fmac_f32_e32 v92, v93, v90
	v_fma_f32 v89, -v89, v92, v91
	v_div_fmas_f32 v89, v89, v90, v92
	v_div_fixup_f32 v88, v89, v88, 1.0
	ds_write_b32 v181, v88

.LBB0_227:
	v_add_u32_e32 v89, s86, v214
	v_add_u32_e32 v94, s86, v212
	ds_read_b128 v[90:93], v89 offset:34816
	v_add_u32_e32 v95, 0x19800, v94
	v_add_u32_e32 v98, 0x1a900, v94
	ds_read_b128 v[94:97], v95
	ds_read_b128 v[98:101], v98
	ds_read_b128 v[246:249], v89 offset:39168
	v_add_u32_e32 v102, 0x11000, v89
	v_add_u32_e32 v245, 0x12100, v89
	ds_read_b128 v[250:253], v102
	ds_read_b128 v[102:105], v245
	s_add_i32 s86, s86, 64
	s_cmpk_eq_i32 s86, 0x100
	s_waitcnt lgkmcnt(4)
	v_mfma_f32_16x16x32_bf16 v[84:87], v[90:93], v[94:97], v[84:87]
	s_waitcnt lgkmcnt(3)
	v_mfma_f32_16x16x32_bf16 v[80:83], v[90:93], v[98:101], v[80:83]
	s_waitcnt lgkmcnt(2)
	v_mfma_f32_16x16x32_bf16 v[76:79], v[246:249], v[94:97], v[76:79]
	v_mfma_f32_16x16x32_bf16 v[72:75], v[246:249], v[98:101], v[72:75]
	s_waitcnt lgkmcnt(1)
	v_mfma_f32_16x16x32_bf16 v[56:59], v[250:253], v[94:97], v[56:59]
	v_mfma_f32_16x16x32_bf16 v[60:63], v[250:253], v[98:101], v[60:63]
	s_waitcnt lgkmcnt(0)
	v_mfma_f32_16x16x32_bf16 v[64:67], v[102:105], v[94:97], v[64:67]
	v_mfma_f32_16x16x32_bf16 v[68:71], v[102:105], v[98:101], v[68:71]
	s_cbranch_scc0 .LBB0_227
	ds_read_b128 v[90:93], v216
	ds_read_b128 v[94:97], v216 offset:16
	ds_read_b128 v[98:101], v216 offset:32
	ds_read_b128 v[102:105], v216 offset:48
	s_lshl_b32 s84, s84, 7
	s_sub_i32 s90, s94, s84
	s_and_b64 s[86:87], s[2:3], exec
	s_waitcnt lgkmcnt(3)
	v_lshlrev_b32_e32 v89, 16, v90
	v_and_b32_e32 v90, 0xffff0000, v90
	v_add_f32_e32 v89, v89, v90
	v_lshlrev_b32_e32 v90, 16, v91
	v_and_b32_e32 v91, 0xffff0000, v91
	v_add_f32_e32 v90, v90, v91
	v_add_f32_e32 v89, v89, v90
	v_lshlrev_b32_e32 v90, 16, v92
	v_and_b32_e32 v91, 0xffff0000, v92
	v_add_f32_e32 v90, v90, v91
	v_add_f32_e32 v89, v90, v89
	v_lshlrev_b32_e32 v90, 16, v93
	v_and_b32_e32 v91, 0xffff0000, v93
	v_add_f32_e32 v90, v90, v91
	v_add_f32_e32 v89, v90, v89
	s_waitcnt lgkmcnt(2)
	v_lshlrev_b32_e32 v90, 16, v94
	v_and_b32_e32 v91, 0xffff0000, v94
	v_add_f32_e32 v90, v90, v91
	v_lshlrev_b32_e32 v91, 16, v95
	v_and_b32_e32 v92, 0xffff0000, v95
	v_add_f32_e32 v91, v91, v92
	v_add_f32_e32 v90, v90, v91
	v_lshlrev_b32_e32 v91, 16, v96
	v_and_b32_e32 v92, 0xffff0000, v96
	v_add_f32_e32 v91, v91, v92
	v_add_f32_e32 v90, v91, v90
	v_lshlrev_b32_e32 v91, 16, v97
	v_and_b32_e32 v92, 0xffff0000, v97
	v_add_f32_e32 v91, v91, v92
	v_add_f32_e32 v89, 0, v89
	v_add_f32_e32 v90, v91, v90
	v_add_f32_e32 v89, v89, v90
	s_waitcnt lgkmcnt(1)
	v_lshlrev_b32_e32 v90, 16, v98
	v_and_b32_e32 v91, 0xffff0000, v98
	v_add_f32_e32 v90, v90, v91
	v_lshlrev_b32_e32 v91, 16, v99
	v_and_b32_e32 v92, 0xffff0000, v99
	v_add_f32_e32 v91, v91, v92
	v_add_f32_e32 v90, v90, v91
	v_lshlrev_b32_e32 v91, 16, v100
	v_and_b32_e32 v92, 0xffff0000, v100
	v_add_f32_e32 v91, v91, v92
	v_add_f32_e32 v90, v91, v90
	v_lshlrev_b32_e32 v91, 16, v101
	v_and_b32_e32 v92, 0xffff0000, v101
	v_add_f32_e32 v91, v91, v92
	v_add_f32_e32 v90, v91, v90
	v_add_f32_e32 v89, v89, v90
	s_waitcnt lgkmcnt(0)
	v_lshlrev_b32_e32 v90, 16, v102
	v_and_b32_e32 v91, 0xffff0000, v102
	v_add_f32_e32 v90, v90, v91
	v_lshlrev_b32_e32 v91, 16, v103
	v_and_b32_e32 v92, 0xffff0000, v103
	v_add_f32_e32 v91, v91, v92
	v_add_f32_e32 v90, v90, v91
	v_lshlrev_b32_e32 v91, 16, v104
	v_and_b32_e32 v92, 0xffff0000, v104
	v_add_f32_e32 v91, v91, v92
	v_add_f32_e32 v90, v91, v90
	v_lshlrev_b32_e32 v91, 16, v105
	v_and_b32_e32 v92, 0xffff0000, v105
	v_add_f32_e32 v91, v91, v92
	s_cselect_b32 s84, s84, s90
	ds_read_b128 v[92:95], v182
	s_add_i32 s84, s84, s89
	v_or_b32_e32 v96, s84, v200
	v_ashrrev_i32_e32 v97, 31, v96
	v_lshlrev_b64 v[96:97], 11, v[96:97]
	v_lshl_add_u64 v[100:101], v[146:147], 0, v[96:97]
	ds_read_b128 v[96:99], v182 offset:64
	s_waitcnt lgkmcnt(1)
	v_mul_f32_e32 v84, v84, v92
	v_mul_f32_e32 v80, v80, v92
	v_cvt_pk_bf16_f32 v84, v84, v84
	global_store_short v[100:101], v84, off
	v_cvt_pk_bf16_f32 v80, v80, v80
	global_store_short v[100:101], v80, off offset:32
	v_or_b32_e32 v100, s84, v201
	v_ashrrev_i32_e32 v101, 31, v100
	v_lshlrev_b64 v[100:101], 11, v[100:101]
	v_mul_f32_e32 v80, v85, v93
	v_lshl_add_u64 v[100:101], v[146:147], 0, v[100:101]
	v_cvt_pk_bf16_f32 v80, v80, v80
	global_store_short v[100:101], v80, off
	v_mul_f32_e32 v80, v81, v93
	v_cvt_pk_bf16_f32 v80, v80, v80
	global_store_short v[100:101], v80, off offset:32
	v_or_b32_e32 v80, s84, v203
	v_ashrrev_i32_e32 v81, 31, v80
	v_lshlrev_b64 v[80:81], 11, v[80:81]
	v_lshl_add_u64 v[80:81], v[146:147], 0, v[80:81]
	v_mul_f32_e32 v84, v86, v94
	v_mul_f32_e32 v82, v82, v94
	v_cvt_pk_bf16_f32 v84, v84, v84
	global_store_short v[80:81], v84, off
	v_cvt_pk_bf16_f32 v82, v82, v82
	global_store_short v[80:81], v82, off offset:32
	v_or_b32_e32 v80, s84, v204
	v_ashrrev_i32_e32 v81, 31, v80
	v_lshlrev_b64 v[80:81], 11, v[80:81]
	v_mul_f32_e32 v82, v87, v95
	v_lshl_add_u64 v[80:81], v[146:147], 0, v[80:81]
	v_cvt_pk_bf16_f32 v82, v82, v82
	global_store_short v[80:81], v82, off
	v_mul_f32_e32 v82, v83, v95
	v_cvt_pk_bf16_f32 v82, v82, v82
	global_store_short v[80:81], v82, off offset:32
	v_or_b32_e32 v80, s84, v205
	v_ashrrev_i32_e32 v81, 31, v80
	v_lshlrev_b64 v[80:81], 11, v[80:81]
	v_lshl_add_u64 v[80:81], v[146:147], 0, v[80:81]
	s_waitcnt lgkmcnt(0)
	v_mul_f32_e32 v76, v76, v96
	v_mul_f32_e32 v72, v72, v96
	v_cvt_pk_bf16_f32 v76, v76, v76
	global_store_short v[80:81], v76, off
	v_cvt_pk_bf16_f32 v72, v72, v72
	global_store_short v[80:81], v72, off offset:32
	v_or_b32_e32 v80, s84, v206
	v_ashrrev_i32_e32 v81, 31, v80
	v_lshlrev_b64 v[80:81], 11, v[80:81]
	v_mul_f32_e32 v72, v77, v97
	v_add_f32_e32 v90, v91, v90
	v_lshl_add_u64 v[80:81], v[146:147], 0, v[80:81]
	v_cvt_pk_bf16_f32 v72, v72, v72
	v_add_f32_e32 v89, v89, v90
	global_store_short v[80:81], v72, off
	v_mul_f32_e32 v72, v73, v97
	s_nop 1
	v_add_f32_dpp v89, v89, v89 quad_perm:[1,0,3,2] row_mask:0xf bank_mask:0xf
	v_cvt_pk_bf16_f32 v72, v72, v72
	global_store_short v[80:81], v72, off offset:32
	v_or_b32_e32 v72, s84, v207
	v_ashrrev_i32_e32 v73, 31, v72
	v_lshlrev_b64 v[72:73], 11, v[72:73]
	v_lshl_add_u64 v[72:73], v[146:147], 0, v[72:73]
	v_mul_f32_e32 v76, v78, v98
	v_mul_f32_e32 v74, v74, v98
	s_waitcnt lgkmcnt(0)
	s_nop 0
	v_cvt_pk_bf16_f32 v76, v76, v76
	global_store_short v[72:73], v76, off
	v_cvt_pk_bf16_f32 v74, v74, v74
	global_store_short v[72:73], v74, off offset:32
	v_or_b32_e32 v72, s84, v208
	v_mov_b32_dpp v90, v89 quad_perm:[2,3,0,1] row_mask:0xf bank_mask:0xf
	v_ashrrev_i32_e32 v73, 31, v72
	v_lshlrev_b64 v[72:73], 11, v[72:73]
	v_mul_f32_e32 v74, v79, v99
	v_lshl_add_u64 v[72:73], v[146:147], 0, v[72:73]
	v_cvt_pk_bf16_f32 v74, v74, v74
	global_store_short v[72:73], v74, off
	v_mul_f32_e32 v74, v75, v99
	v_cvt_pk_bf16_f32 v76, v64, v65
	v_cvt_pk_bf16_f32 v74, v74, v74
	global_store_short v[72:73], v74, off offset:32
	s_waitcnt lgkmcnt(0)
	s_barrier
	ds_read_b32 v245, v134
	v_cvt_pk_bf16_f32 v72, v56, v57
	v_cvt_pk_bf16_f32 v73, v58, v59
	v_cvt_pk_bf16_f32 v77, v66, v67
	ds_write2_b64 v217, v[72:73], v[76:77] offset1:4
	v_add_u32_e32 v76, 0x1000, v217
	v_cvt_pk_bf16_f32 v74, v60, v61
	v_cvt_pk_bf16_f32 v75, v62, v63
	v_cvt_pk_bf16_f32 v72, v68, v69
	v_cvt_pk_bf16_f32 v73, v70, v71
	ds_write2_b64 v76, v[74:75], v[72:73] offset0:32 offset1:36
	s_and_saveexec_b64 s[86:87], s[6:7]
	s_cbranch_execz .LBB0_201
	s_waitcnt lgkmcnt(2)
	v_add_f32_e32 v72, v89, v90
	v_mov_b32_e32 v73, v245
	v_fmac_f32_e32 v72, v88, v73
	ds_write_b32 v134, v72
	s_branch .LBB0_201
